# hand-written LN1 phase: all Y/gamma/beta/modulation loads issued up front per wave, permlane+DPP wave sums, counted waits
# speedup vs baseline: 1.0451x; 1.0226x over previous
.LBB0_459:
	v_ashrrev_i32_e32 v113, 31, v112
	s_waitcnt vmcnt(0) lgkmcnt(0)
	v_lshlrev_b64 v[74:75], 11, v[112:113]
	v_lshl_add_u64 v[74:75], v[90:91], 0, v[74:75]
	v_pk_mul_f32 v[44:45], v[92:93], v[44:45]
	v_pk_mul_f32 v[42:43], v[88:89], v[42:43]
	flat_store_dwordx4 v[74:75], v[42:45] sc1
	v_add_u32_e32 v0, v126, v127
	s_mov_b32 s71, 1
	v_pk_mul_f32 v[44:45], v[92:93], v[48:49]
	v_pk_mul_f32 v[42:43], v[88:89], v[46:47]
	flat_store_dwordx4 v[74:75], v[42:45] offset:64 sc1
	s_mov_b64 s[68:69], 0
	s_andn2_b64 vcc, exec, s[74:75]
	v_pk_mul_f32 v[44:45], v[92:93], v[52:53]
	v_pk_mul_f32 v[42:43], v[88:89], v[50:51]
	flat_store_dwordx4 v[74:75], v[42:45] offset:128 sc1
	v_add_u32_e32 v52, v126, v128
	s_mov_b64 s[74:75], -1
	v_pk_mul_f32 v[44:45], v[92:93], v[56:57]
	v_pk_mul_f32 v[42:43], v[88:89], v[54:55]
	flat_store_dwordx4 v[74:75], v[42:45] offset:192 sc1
	s_nop 1
	v_pk_mul_f32 v[44:45], v[92:93], v[60:61]
	v_pk_mul_f32 v[42:43], v[88:89], v[58:59]
	flat_store_dwordx4 v[74:75], v[42:45] offset:256 sc1
	s_nop 1
	v_pk_mul_f32 v[44:45], v[92:93], v[64:65]
	v_pk_mul_f32 v[42:43], v[88:89], v[62:63]
	flat_store_dwordx4 v[74:75], v[42:45] offset:320 sc1
	s_nop 1
	v_pk_mul_f32 v[44:45], v[92:93], v[68:69]
	v_pk_mul_f32 v[42:43], v[88:89], v[66:67]
	flat_store_dwordx4 v[74:75], v[42:45] offset:384 sc1
	s_nop 1
	v_pk_mul_f32 v[44:45], v[92:93], v[72:73]
	v_pk_mul_f32 v[42:43], v[88:89], v[70:71]
	flat_store_dwordx4 v[74:75], v[42:45] offset:448 sc1
	s_nop 1
	v_add_u32_e32 v44, v131, v116
	ds_read_b64_tr_b16 v[42:43], v44 offset:32768
	ds_read_b64_tr_b16 v[44:45], v44 offset:36864
	ds_read_b64_tr_b16 v[46:47], v0
	ds_read_b64_tr_b16 v[48:49], v0 offset:2048
	ds_read_b64_tr_b16 v[50:51], v52
	ds_read_b64_tr_b16 v[52:53], v52 offset:2048
	v_add_u32_e32 v0, v132, v127
	ds_read_b64_tr_b16 v[54:55], v0
	ds_read_b64_tr_b16 v[56:57], v0 offset:2048
	v_add_u32_e32 v0, v126, v129
	s_waitcnt lgkmcnt(0)
	v_mfma_f32_16x16x32_bf16 v[30:33], v[42:45], v[46:49], v[30:33]
	ds_read_b64_tr_b16 v[46:47], v0
	ds_read_b64_tr_b16 v[48:49], v0 offset:2048
	v_add_u32_e32 v0, v126, v130
	v_mfma_f32_16x16x32_bf16 v[34:37], v[42:45], v[50:53], v[34:37]
	ds_read_b64_tr_b16 v[50:51], v0
	ds_read_b64_tr_b16 v[52:53], v0 offset:2048
	v_add_u32_e32 v0, v132, v128
	s_waitcnt lgkmcnt(0)
	v_mfma_f32_16x16x32_bf16 v[38:41], v[42:45], v[46:49], v[38:41]
	ds_read_b64_tr_b16 v[46:47], v175 offset:32768
	ds_read_b64_tr_b16 v[48:49], v175 offset:36864
	v_mfma_f32_16x16x32_bf16 v[26:29], v[42:45], v[50:53], v[26:29]
	ds_read_b64_tr_b16 v[42:43], v0
	ds_read_b64_tr_b16 v[44:45], v0 offset:2048
	v_add_u32_e32 v0, v132, v130
	v_add_u32_e32 v50, v132, v129
	ds_read_b64_tr_b16 v[52:53], v0 offset:2048
	s_waitcnt lgkmcnt(0)
	v_mfma_f32_16x16x32_bf16 v[30:33], v[46:49], v[54:57], v[30:33]
	ds_read_b64_tr_b16 v[54:55], v50
	ds_read_b64_tr_b16 v[56:57], v50 offset:2048
	ds_read_b64_tr_b16 v[50:51], v0
	v_add_u32_e32 v0, v133, v127
	v_mfma_f32_16x16x32_bf16 v[34:37], v[46:49], v[42:45], v[34:37]
	ds_read_b64_tr_b16 v[42:43], v176 offset:32768
	ds_read_b64_tr_b16 v[44:45], v176 offset:36864
	s_waitcnt lgkmcnt(0)
	v_mfma_f32_16x16x32_bf16 v[26:29], v[46:49], v[50:53], v[26:29]
	v_add_u32_e32 v52, v133, v128
	v_mfma_f32_16x16x32_bf16 v[38:41], v[46:49], v[54:57], v[38:41]
	ds_read_b64_tr_b16 v[46:47], v0
	ds_read_b64_tr_b16 v[48:49], v0 offset:2048
	ds_read_b64_tr_b16 v[50:51], v52
	ds_read_b64_tr_b16 v[52:53], v52 offset:2048
	v_add_u32_e32 v0, v134, v127
	ds_read_b64_tr_b16 v[54:55], v0
	ds_read_b64_tr_b16 v[56:57], v0 offset:2048
	v_add_u32_e32 v0, v133, v129
	s_waitcnt lgkmcnt(0)
	v_mfma_f32_16x16x32_bf16 v[30:33], v[42:45], v[46:49], v[30:33]
	ds_read_b64_tr_b16 v[46:47], v0
	ds_read_b64_tr_b16 v[48:49], v0 offset:2048
	v_add_u32_e32 v0, v133, v130
	v_mfma_f32_16x16x32_bf16 v[34:37], v[42:45], v[50:53], v[34:37]
	ds_read_b64_tr_b16 v[50:51], v0
	ds_read_b64_tr_b16 v[52:53], v0 offset:2048
	v_add_u32_e32 v0, v134, v128
	s_waitcnt lgkmcnt(0)
	v_mfma_f32_16x16x32_bf16 v[38:41], v[42:45], v[46:49], v[38:41]
	ds_read_b64_tr_b16 v[46:47], v177 offset:32768
	ds_read_b64_tr_b16 v[48:49], v177 offset:36864
	v_mfma_f32_16x16x32_bf16 v[42:45], v[42:45], v[50:53], v[26:29]
	ds_read_b64_tr_b16 v[50:51], v0
	ds_read_b64_tr_b16 v[52:53], v0 offset:2048
	v_add_u32_e32 v0, v134, v130
	ds_read_b64_tr_b16 v[58:59], v0 offset:2048
	s_waitcnt lgkmcnt(0)
	v_mfma_f32_16x16x32_bf16 v[26:29], v[46:49], v[54:57], v[30:33]
	s_nop 2
	v_add_u32_e32 v32, v134, v129
	ds_read_b64_tr_b16 v[30:31], v32
	ds_read_b64_tr_b16 v[32:33], v32 offset:2048
	ds_read_b64_tr_b16 v[56:57], v0
	v_mfma_f32_16x16x32_bf16 v[34:37], v[46:49], v[50:53], v[34:37]
	s_waitcnt lgkmcnt(0)
	v_mfma_f32_16x16x32_bf16 v[38:41], v[46:49], v[30:33], v[38:41]
	v_mfma_f32_16x16x32_bf16 v[42:45], v[46:49], v[56:59], v[42:45]
	s_cbranch_vccz .LBB0_486

.LBB0_486:
	v_readlane_b32 s5, v255, 12
	s_lshl_b32 s2, s5, 2
	v_readlane_b32 s3, v255, 7
	s_or_b32 s2, s2, s3
	v_readlane_b32 s56, v254, 39
	s_or_b32 s2, s2, s70
	s_mov_b32 s64, 0
	v_readlane_b32 s60, v254, 43
	v_readlane_b32 s61, v254, 44
	s_lshl_b32 s2, s2, 2
	v_readlane_b32 s6, v255, 17
	s_xor_b64 s[0:1], s[64:65], s[60:61]
	s_or_b32 s64, s2, s6
	s_lshl_b64 s[2:3], s[64:65], 15
	s_add_u32 s2, s0, s2
	s_addc_u32 s3, s1, s3
	v_readlane_b32 s0, v255, 15
	v_readlane_b32 s1, v255, 16
	s_ashr_i32 s1, s0, 31
	s_lshl_b64 s[0:1], s[0:1], 2
	s_add_u32 s0, s2, s0
	s_addc_u32 s1, s3, s1
	v_lshlrev_b32_e32 v0, 2, v82
	v_lshl_add_u64 v[2:3], s[0:1], 0, v[0:1]
	v_lshlrev_b32_e32 v0, 2, v114
	v_lshl_add_u64 v[2:3], v[2:3], 0, v[0:1]
	s_mov_b32 s0, 0x4800000
	v_add_co_u32_e32 v4, vcc, s0, v2
	s_mov_b32 s0, 0x4802000
	s_nop 0
	v_addc_co_u32_e32 v5, vcc, 0, v3, vcc
	flat_store_dwordx4 v[4:5], v[26:29]
	v_add_co_u32_e32 v4, vcc, s0, v2
	v_readlane_b32 s57, v254, 40
	s_nop 0
	v_addc_co_u32_e32 v5, vcc, 0, v3, vcc
	flat_store_dwordx4 v[4:5], v[34:37]
	v_add_co_u32_e32 v4, vcc, 0x4804000, v2
	v_readlane_b32 s58, v254, 41
	s_nop 0
	v_addc_co_u32_e32 v5, vcc, 0, v3, vcc
	v_add_co_u32_e32 v2, vcc, 0x4806000, v2
	flat_store_dwordx4 v[4:5], v[38:41]
	s_nop 0
	v_addc_co_u32_e32 v3, vcc, 0, v3, vcc
	flat_store_dwordx4 v[2:3], v[42:45]
	s_waitcnt vmcnt(0)
	v_readlane_b32 s59, v254, 42
	v_readlane_b32 s62, v254, 45
	v_readlane_b32 s63, v254, 46
	v_cmp_eq_u32_e32 vcc, 0, v83
	s_waitcnt lgkmcnt(0)
	s_barrier
	s_and_saveexec_b64 s[0:1], vcc
	s_xor_b64 s[0:1], exec, s[0:1]
	s_cbranch_execz .LBB0_488
	v_readlane_b32 s4, v254, 59
	s_waitcnt vmcnt(0)
	s_waitcnt vmcnt(0)
	s_mov_b32 s64, 0
	s_add_i32 s4, s5, s4
	s_xor_b64 s[2:3], s[64:65], s[62:63]
	s_lshl_b32 s64, s4, 2
	s_lshl_b64 s[4:5], s[64:65], 2
	s_add_u32 s2, s2, s4
	s_addc_u32 s3, s3, s5
	s_lshl_b32 s4, s6, 2
	s_add_u32 s2, s2, s4
	s_addc_u32 s3, s3, 0
	v_mov_b32_e32 v0, s2
	v_add_co_u32_e32 v2, vcc, 0xee3e000, v0
	v_mov_b32_e32 v0, s3
	s_nop 0
	v_addc_co_u32_e32 v3, vcc, 0, v0, vcc
	flat_atomic_add v[2:3], v237 offset:256

.LBB0_524:
	v_ashrrev_i32_e32 v105, 31, v104
	s_waitcnt vmcnt(0) lgkmcnt(0)
	v_lshlrev_b64 v[74:75], 11, v[104:105]
	v_lshl_add_u64 v[74:75], v[92:93], 0, v[74:75]
	v_pk_mul_f32 v[44:45], v[94:95], v[44:45]
	v_pk_mul_f32 v[42:43], v[90:91], v[42:43]
	flat_store_dwordx4 v[74:75], v[42:45] sc1
	s_add_i32 s1, s1, -1
	s_add_i32 s0, s0, 1
	v_pk_mul_f32 v[44:45], v[94:95], v[48:49]
	v_pk_mul_f32 v[42:43], v[90:91], v[46:47]
	flat_store_dwordx4 v[74:75], v[42:45] offset:64 sc1
	v_add_u32_e32 v48, v131, v132
	s_cmp_eq_u32 s1, -1
	v_pk_mul_f32 v[44:45], v[94:95], v[52:53]
	v_pk_mul_f32 v[42:43], v[90:91], v[50:51]
	flat_store_dwordx4 v[74:75], v[42:45] offset:128 sc1
	v_add_u32_e32 v52, v131, v133
	s_nop 0
	v_pk_mul_f32 v[44:45], v[94:95], v[56:57]
	v_pk_mul_f32 v[42:43], v[90:91], v[54:55]
	flat_store_dwordx4 v[74:75], v[42:45] offset:192 sc1
	v_add_u32_e32 v56, v137, v132
	s_nop 0
	v_pk_mul_f32 v[44:45], v[94:95], v[60:61]
	v_pk_mul_f32 v[42:43], v[90:91], v[58:59]
	flat_store_dwordx4 v[74:75], v[42:45] offset:256 sc1
	s_nop 1
	v_pk_mul_f32 v[44:45], v[94:95], v[64:65]
	v_pk_mul_f32 v[42:43], v[90:91], v[62:63]
	flat_store_dwordx4 v[74:75], v[42:45] offset:320 sc1
	s_nop 1
	v_pk_mul_f32 v[44:45], v[94:95], v[68:69]
	v_pk_mul_f32 v[42:43], v[90:91], v[66:67]
	flat_store_dwordx4 v[74:75], v[42:45] offset:384 sc1
	s_nop 1
	v_pk_mul_f32 v[44:45], v[94:95], v[72:73]
	v_pk_mul_f32 v[42:43], v[90:91], v[70:71]
	flat_store_dwordx4 v[74:75], v[42:45] offset:448 sc1
	s_nop 1
	v_add_u32_e32 v44, v136, v113
	ds_read_b64_tr_b16 v[42:43], v44 offset:32768
	ds_read_b64_tr_b16 v[44:45], v44 offset:36864
	ds_read_b64_tr_b16 v[46:47], v48
	ds_read_b64_tr_b16 v[48:49], v48 offset:2048
	ds_read_b64_tr_b16 v[50:51], v52
	ds_read_b64_tr_b16 v[52:53], v52 offset:2048
	s_waitcnt lgkmcnt(0)
	v_mfma_f32_16x16x32_bf16 v[38:41], v[42:45], v[46:49], v[38:41]
	v_add_u32_e32 v48, v131, v134
	ds_read_b64_tr_b16 v[54:55], v56
	ds_read_b64_tr_b16 v[56:57], v56 offset:2048
	ds_read_b64_tr_b16 v[46:47], v48
	ds_read_b64_tr_b16 v[48:49], v48 offset:2048
	v_mfma_f32_16x16x32_bf16 v[34:37], v[42:45], v[50:53], v[34:37]
	v_add_u32_e32 v52, v131, v135
	ds_read_b64_tr_b16 v[50:51], v52
	ds_read_b64_tr_b16 v[52:53], v52 offset:2048
	s_waitcnt lgkmcnt(0)
	v_mfma_f32_16x16x32_bf16 v[30:33], v[42:45], v[46:49], v[30:33]
	ds_read_b64_tr_b16 v[46:47], v173 offset:32768
	ds_read_b64_tr_b16 v[48:49], v173 offset:36864
	v_mfma_f32_16x16x32_bf16 v[26:29], v[42:45], v[50:53], v[26:29]
	v_add_u32_e32 v44, v137, v133
	ds_read_b64_tr_b16 v[42:43], v44
	ds_read_b64_tr_b16 v[44:45], v44 offset:2048
	v_add_u32_e32 v50, v137, v135
	v_add_u32_e32 v51, v137, v134
	ds_read_b64_tr_b16 v[52:53], v50 offset:2048
	s_waitcnt lgkmcnt(0)
	v_mfma_f32_16x16x32_bf16 v[38:41], v[46:49], v[54:57], v[38:41]
	ds_read_b64_tr_b16 v[54:55], v51
	ds_read_b64_tr_b16 v[56:57], v51 offset:2048
	ds_read_b64_tr_b16 v[50:51], v50
	v_mfma_f32_16x16x32_bf16 v[34:37], v[46:49], v[42:45], v[34:37]
	ds_read_b64_tr_b16 v[42:43], v174 offset:32768
	ds_read_b64_tr_b16 v[44:45], v174 offset:36864
	s_waitcnt lgkmcnt(0)
	v_mfma_f32_16x16x32_bf16 v[30:33], v[46:49], v[54:57], v[30:33]
	v_add_u32_e32 v56, v139, v132
	v_mfma_f32_16x16x32_bf16 v[26:29], v[46:49], v[50:53], v[26:29]
	v_add_u32_e32 v48, v138, v132
	v_add_u32_e32 v52, v138, v133
	ds_read_b64_tr_b16 v[46:47], v48
	ds_read_b64_tr_b16 v[48:49], v48 offset:2048
	ds_read_b64_tr_b16 v[50:51], v52
	ds_read_b64_tr_b16 v[52:53], v52 offset:2048
	s_waitcnt lgkmcnt(0)
	v_mfma_f32_16x16x32_bf16 v[38:41], v[42:45], v[46:49], v[38:41]
	v_add_u32_e32 v48, v138, v134
	ds_read_b64_tr_b16 v[54:55], v56
	ds_read_b64_tr_b16 v[56:57], v56 offset:2048
	ds_read_b64_tr_b16 v[46:47], v48
	ds_read_b64_tr_b16 v[48:49], v48 offset:2048
	v_mfma_f32_16x16x32_bf16 v[34:37], v[42:45], v[50:53], v[34:37]
	v_add_u32_e32 v52, v138, v135
	ds_read_b64_tr_b16 v[50:51], v52
	ds_read_b64_tr_b16 v[52:53], v52 offset:2048
	s_waitcnt lgkmcnt(0)
	v_mfma_f32_16x16x32_bf16 v[30:33], v[42:45], v[46:49], v[30:33]
	ds_read_b64_tr_b16 v[46:47], v175 offset:32768
	ds_read_b64_tr_b16 v[48:49], v175 offset:36864
	v_mfma_f32_16x16x32_bf16 v[26:29], v[42:45], v[50:53], v[26:29]
	v_add_u32_e32 v44, v139, v133
	v_add_u32_e32 v50, v139, v135
	v_add_u32_e32 v51, v139, v134
	ds_read_b64_tr_b16 v[42:43], v44
	ds_read_b64_tr_b16 v[44:45], v44 offset:2048
	ds_read_b64_tr_b16 v[52:53], v50 offset:2048
	s_waitcnt lgkmcnt(0)
	v_mfma_f32_16x16x32_bf16 v[38:41], v[46:49], v[54:57], v[38:41]
	ds_read_b64_tr_b16 v[54:55], v51
	ds_read_b64_tr_b16 v[56:57], v51 offset:2048
	ds_read_b64_tr_b16 v[50:51], v50
	v_mfma_f32_16x16x32_bf16 v[34:37], v[46:49], v[42:45], v[34:37]
	s_waitcnt lgkmcnt(0)
	v_mfma_f32_16x16x32_bf16 v[30:33], v[46:49], v[54:57], v[30:33]
	v_mfma_f32_16x16x32_bf16 v[26:29], v[46:49], v[50:53], v[26:29]
	s_cbranch_scc1 .LBB0_551

.LBB0_553:
	s_waitcnt vmcnt(0)
	s_waitcnt lgkmcnt(0)
	s_barrier
	v_cmp_eq_u32_e32 vcc, 0, v106
	s_mov_b64 s[0:1], exec
	v_readlane_b32 s72, v254, 33
	s_and_b64 s[2:3], s[0:1], vcc
	v_readlane_b32 s73, v254, 34
	v_readlane_b32 s76, v254, 37
	s_xor_b64 s[0:1], s[2:3], s[0:1]
	v_readlane_b32 s90, v254, 32
	v_readlane_b32 s91, v254, 35
	v_readlane_b32 s74, v254, 36
	v_readlane_b32 s77, v254, 38
	v_readlane_b32 s75, v254, 47
	v_readlane_b32 s78, v254, 48
	v_readlane_b32 s79, v254, 49
	v_readlane_b32 s73, v254, 50
	v_readlane_b32 s80, v254, 51
	s_mov_b32 s70, 0x5a3e000
	s_movk_i32 s81, 0x2000
	s_mov_b32 s84, 0x12000
	s_mov_b32 s85, 0x14000
	s_mov_b32 s88, 0x16000
	s_movk_i32 s89, 0x4000
	s_movk_i32 s92, 0x6000
	s_movk_i32 s93, 0x3000
	s_mov_b32 s94, 0x18000
	s_mov_b32 s95, 0x1a000
	s_mov_b32 s96, 0x8000
	s_mov_b32 s97, 0xa000
	s_mov_b32 s69, 0x1c000
	s_mov_b32 s68, 0x1e000
	s_movk_i32 s66, 0x1e00
	s_mov_b32 s67, 0x800000
	s_mov_b64 exec, s[2:3]
	s_cbranch_execz .LBB0_359
	v_readlane_b32 s4, v254, 59
	v_readlane_b32 s5, v255, 15
	s_add_i32 s4, s5, s4
	s_lshl_b32 s4, s4, 2
	s_ashr_i32 s5, s4, 31
	s_waitcnt vmcnt(0)
	s_waitcnt vmcnt(0)
	s_mov_b32 s64, 0
	s_xor_b64 s[2:3], s[64:65], s[62:63]
	s_lshl_b64 s[4:5], s[4:5], 2
	s_add_u32 s2, s2, s4
	s_addc_u32 s3, s3, s5
	s_lshl_b32 s4, s6, 2
	s_add_u32 s2, s2, s4
	s_addc_u32 s3, s3, 0
	v_mov_b32_e32 v0, s2
	v_add_co_u32_e32 v2, vcc, 0xee3e000, v0
	v_mov_b32_e32 v0, s3
	s_nop 0
	v_addc_co_u32_e32 v3, vcc, 0, v0, vcc
	flat_atomic_add v[2:3], v237 offset:256
	s_branch .LBB0_359

.LBB0_1029:
	s_or_b64 exec, exec, s[0:1]
	s_waitcnt lgkmcnt(0)
	s_barrier
	s_mov_b64 s[6:7], exec
	s_mov_b32 s83, s71
	v_readlane_b32 s4, v251, 0
	v_readlane_b32 s5, v251, 1
	v_readlane_b32 s22, v254, 53
	v_readlane_b32 s0, v254, 6
	s_nop 4
	s_load_dwordx4 s[24:27], s[4:5], 0xb8
	s_load_dwordx2 s[10:11], s[4:5], 0xe8
	s_lshr_b32 s1, s91, 6
	s_lshl_b32 s1, s1, 2
	s_add_i32 s0, s0, s1
	s_mov_b32 s46, 0x3a800000
	s_mov_b32 s29, 0x800000
	s_mov_b32 s28, 0xffff0000
	v_lshlrev_b32_e32 v2, 4, v230
	v_add_u32_e32 v3, 0x1000, v2
	v_lshlrev_b32_e32 v134, 5, v230
	v_add_u32_e32 v135, 0x1000, v134
	v_add_u32_e32 v136, 0x2000, v134
	v_add_u32_e32 v137, 0x3000, v134
	v_mov_b32_e32 v154, 0x3727c5ac
	s_lshl_b32 s23, s22, 12
	s_mul_i32 s30, s22, 0x1e000
	s_add_i32 s30, s30, 0x4a00000
	s_waitcnt lgkmcnt(0)
	s_add_u32 s14, s24, s23
	s_addc_u32 s15, s25, 0
	s_add_u32 s16, s26, s23
	s_addc_u32 s17, s27, 0
.Lln1_loop:
	s_waitcnt vmcnt(0)
	s_cmp_ge_i32 s0, s80
	s_cbranch_scc1 .Lln1_end
	s_lshr_b32 s1, s0, 10
	s_sub_i32 s1, s1, 3
	s_cmp_lt_u32 s0, 0x1000
	s_cselect_b32 s1, 0, s1
	s_mul_i32 s1, s1, 0x6000
	s_add_i32 s1, s1, s30
	s_add_u32 s18, s62, s1
	s_addc_u32 s19, s63, 0
	s_add_u32 s20, s18, 0x3000
	s_addc_u32 s21, s19, 0
	s_add_u32 s18, s18, 0x4000
	s_addc_u32 s19, s19, 0
	s_lshl_b32 s1, s0, 11
	s_add_u32 s8, s62, s1
	s_addc_u32 s9, s63, 0
	s_add_u32 s12, s8, 0x4a3e000
	s_addc_u32 s13, s9, 0
	s_add_u32 s8, s8, 0xc23e000
	s_addc_u32 s9, s9, 0
	s_lshl_b32 s1, s0, 12
	s_add_u32 s4, s10, s1
	s_addc_u32 s5, s11, 0
	global_load_dwordx4 v[8:11], v2, s[8:9]
	global_load_dwordx4 v[16:19], v2, s[8:9] offset:1024
	global_load_dwordx4 v[24:27], v2, s[8:9] offset:2048
	global_load_dwordx4 v[32:35], v2, s[8:9] offset:3072
	global_load_dwordx4 v[40:43], v3, s[8:9]
	global_load_dwordx4 v[48:51], v3, s[8:9] offset:1024
	global_load_dwordx4 v[56:59], v3, s[8:9] offset:2048
	global_load_dwordx4 v[64:67], v3, s[8:9] offset:3072
	global_load_dwordx4 v[68:71], v134, s[14:15]
	global_load_dwordx4 v[72:75], v134, s[14:15] offset:16
	global_load_dwordx4 v[76:79], v134, s[14:15] offset:2048
	global_load_dwordx4 v[80:83], v134, s[14:15] offset:2064
	global_load_dwordx4 v[84:87], v134, s[16:17]
	global_load_dwordx4 v[88:91], v134, s[16:17] offset:16
	global_load_dwordx4 v[92:95], v134, s[16:17] offset:2048
	global_load_dwordx4 v[96:99], v134, s[16:17] offset:2064
	global_load_dwordx4 v[100:103], v134, s[18:19]
	global_load_dwordx4 v[104:107], v134, s[18:19] offset:16
	global_load_dwordx4 v[108:111], v134, s[18:19] offset:2048
	global_load_dwordx4 v[112:115], v134, s[18:19] offset:2064
	global_load_dwordx4 v[118:121], v134, s[20:21]
	global_load_dwordx4 v[122:125], v134, s[20:21] offset:16
	global_load_dwordx4 v[126:129], v134, s[20:21] offset:2048
	global_load_dwordx4 v[130:133], v134, s[20:21] offset:2064
	s_waitcnt vmcnt(22)
	v_lshlrev_b32_e32 v4, 16, v8
	v_and_b32_e32 v5, s28, v8
	v_lshlrev_b32_e32 v6, 16, v9
	v_and_b32_e32 v7, s28, v9
	v_lshlrev_b32_e32 v8, 16, v10
	v_and_b32_e32 v9, s28, v10
	v_lshlrev_b32_e32 v10, 16, v11
	v_and_b32_e32 v11, s28, v11
	v_lshlrev_b32_e32 v12, 16, v16
	v_and_b32_e32 v13, s28, v16
	v_lshlrev_b32_e32 v14, 16, v17
	v_and_b32_e32 v15, s28, v17
	v_lshlrev_b32_e32 v16, 16, v18
	v_and_b32_e32 v17, s28, v18
	v_lshlrev_b32_e32 v18, 16, v19
	v_and_b32_e32 v19, s28, v19
	v_pk_add_f32 v[138:139], v[4:5], v[6:7]
	v_pk_add_f32 v[138:139], v[138:139], v[8:9]
	v_pk_add_f32 v[138:139], v[138:139], v[10:11]
	v_pk_add_f32 v[138:139], v[138:139], v[12:13]
	v_pk_add_f32 v[138:139], v[138:139], v[14:15]
	v_pk_add_f32 v[138:139], v[138:139], v[16:17]
	v_pk_add_f32 v[138:139], v[138:139], v[18:19]
	s_nop 0
	v_add_f32_e32 v138, v138, v139
	s_waitcnt vmcnt(20)
	v_lshlrev_b32_e32 v20, 16, v24
	v_and_b32_e32 v21, s28, v24
	v_lshlrev_b32_e32 v22, 16, v25
	v_and_b32_e32 v23, s28, v25
	v_lshlrev_b32_e32 v24, 16, v26
	v_and_b32_e32 v25, s28, v26
	v_lshlrev_b32_e32 v26, 16, v27
	v_and_b32_e32 v27, s28, v27
	v_lshlrev_b32_e32 v28, 16, v32
	v_and_b32_e32 v29, s28, v32
	v_lshlrev_b32_e32 v30, 16, v33
	v_and_b32_e32 v31, s28, v33
	v_lshlrev_b32_e32 v32, 16, v34
	v_and_b32_e32 v33, s28, v34
	v_lshlrev_b32_e32 v34, 16, v35
	v_and_b32_e32 v35, s28, v35
	v_pk_add_f32 v[140:141], v[20:21], v[22:23]
	v_pk_add_f32 v[140:141], v[140:141], v[24:25]
	v_pk_add_f32 v[140:141], v[140:141], v[26:27]
	v_pk_add_f32 v[140:141], v[140:141], v[28:29]
	v_pk_add_f32 v[140:141], v[140:141], v[30:31]
	v_pk_add_f32 v[140:141], v[140:141], v[32:33]
	v_pk_add_f32 v[140:141], v[140:141], v[34:35]
	s_nop 0
	v_add_f32_e32 v140, v140, v141
	s_waitcnt vmcnt(18)
	v_lshlrev_b32_e32 v36, 16, v40
	v_and_b32_e32 v37, s28, v40
	v_lshlrev_b32_e32 v38, 16, v41
	v_and_b32_e32 v39, s28, v41
	v_lshlrev_b32_e32 v40, 16, v42
	v_and_b32_e32 v41, s28, v42
	v_lshlrev_b32_e32 v42, 16, v43
	v_and_b32_e32 v43, s28, v43
	v_lshlrev_b32_e32 v44, 16, v48
	v_and_b32_e32 v45, s28, v48
	v_lshlrev_b32_e32 v46, 16, v49
	v_and_b32_e32 v47, s28, v49
	v_lshlrev_b32_e32 v48, 16, v50
	v_and_b32_e32 v49, s28, v50
	v_lshlrev_b32_e32 v50, 16, v51
	v_and_b32_e32 v51, s28, v51
	v_pk_add_f32 v[142:143], v[36:37], v[38:39]
	v_pk_add_f32 v[142:143], v[142:143], v[40:41]
	v_pk_add_f32 v[142:143], v[142:143], v[42:43]
	v_pk_add_f32 v[142:143], v[142:143], v[44:45]
	v_pk_add_f32 v[142:143], v[142:143], v[46:47]
	v_pk_add_f32 v[142:143], v[142:143], v[48:49]
	v_pk_add_f32 v[142:143], v[142:143], v[50:51]
	s_nop 0
	v_add_f32_e32 v142, v142, v143
	s_waitcnt vmcnt(16)
	v_lshlrev_b32_e32 v52, 16, v56
	v_and_b32_e32 v53, s28, v56
	v_lshlrev_b32_e32 v54, 16, v57
	v_and_b32_e32 v55, s28, v57
	v_lshlrev_b32_e32 v56, 16, v58
	v_and_b32_e32 v57, s28, v58
	v_lshlrev_b32_e32 v58, 16, v59
	v_and_b32_e32 v59, s28, v59
	v_lshlrev_b32_e32 v60, 16, v64
	v_and_b32_e32 v61, s28, v64
	v_lshlrev_b32_e32 v62, 16, v65
	v_and_b32_e32 v63, s28, v65
	v_lshlrev_b32_e32 v64, 16, v66
	v_and_b32_e32 v65, s28, v66
	v_lshlrev_b32_e32 v66, 16, v67
	v_and_b32_e32 v67, s28, v67
	v_pk_add_f32 v[144:145], v[52:53], v[54:55]
	v_pk_add_f32 v[144:145], v[144:145], v[56:57]
	v_pk_add_f32 v[144:145], v[144:145], v[58:59]
	v_pk_add_f32 v[144:145], v[144:145], v[60:61]
	v_pk_add_f32 v[144:145], v[144:145], v[62:63]
	v_pk_add_f32 v[144:145], v[144:145], v[64:65]
	v_pk_add_f32 v[144:145], v[144:145], v[66:67]
	s_nop 0
	v_add_f32_e32 v144, v144, v145
	v_mov_b32_e32 v139, v138
	v_mov_b32_e32 v141, v140
	v_mov_b32_e32 v143, v142
	v_mov_b32_e32 v145, v144
	v_permlane32_swap_b32_e32 v138, v139
	v_permlane32_swap_b32_e32 v140, v141
	v_permlane32_swap_b32_e32 v142, v143
	v_permlane32_swap_b32_e32 v144, v145
	v_add_f32_e32 v138, v138, v139
	v_add_f32_e32 v140, v140, v141
	v_add_f32_e32 v142, v142, v143
	v_add_f32_e32 v144, v144, v145
	v_mov_b32_e32 v139, v138
	v_mov_b32_e32 v141, v140
	v_mov_b32_e32 v143, v142
	v_mov_b32_e32 v145, v144
	v_permlane16_swap_b32_e32 v138, v139
	v_permlane16_swap_b32_e32 v140, v141
	v_permlane16_swap_b32_e32 v142, v143
	v_permlane16_swap_b32_e32 v144, v145
	v_add_f32_e32 v138, v138, v139
	v_add_f32_e32 v140, v140, v141
	v_add_f32_e32 v142, v142, v143
	v_add_f32_e32 v144, v144, v145
	v_add_f32_dpp v138, v138, v138 row_ror:8 row_mask:0xf bank_mask:0xf
	v_add_f32_dpp v140, v140, v140 row_ror:8 row_mask:0xf bank_mask:0xf
	v_add_f32_dpp v142, v142, v142 row_ror:8 row_mask:0xf bank_mask:0xf
	v_add_f32_dpp v144, v144, v144 row_ror:8 row_mask:0xf bank_mask:0xf
	v_add_f32_dpp v138, v138, v138 row_ror:4 row_mask:0xf bank_mask:0xf
	v_add_f32_dpp v140, v140, v140 row_ror:4 row_mask:0xf bank_mask:0xf
	v_add_f32_dpp v142, v142, v142 row_ror:4 row_mask:0xf bank_mask:0xf
	v_add_f32_dpp v144, v144, v144 row_ror:4 row_mask:0xf bank_mask:0xf
	v_add_f32_dpp v138, v138, v138 row_ror:2 row_mask:0xf bank_mask:0xf
	v_add_f32_dpp v140, v140, v140 row_ror:2 row_mask:0xf bank_mask:0xf
	v_add_f32_dpp v142, v142, v142 row_ror:2 row_mask:0xf bank_mask:0xf
	v_add_f32_dpp v144, v144, v144 row_ror:2 row_mask:0xf bank_mask:0xf
	v_add_f32_dpp v138, v138, v138 row_ror:1 row_mask:0xf bank_mask:0xf
	v_add_f32_dpp v140, v140, v140 row_ror:1 row_mask:0xf bank_mask:0xf
	v_add_f32_dpp v142, v142, v142 row_ror:1 row_mask:0xf bank_mask:0xf
	v_add_f32_dpp v144, v144, v144 row_ror:1 row_mask:0xf bank_mask:0xf
	v_mul_f32_e32 v138, s46, v138
	v_mul_f32_e32 v140, s46, v140
	v_mul_f32_e32 v142, s46, v142
	v_mul_f32_e32 v144, s46, v144
	v_pk_add_f32 v[4:5], v[4:5], v[138:139] op_sel_hi:[1,0] neg_lo:[0,1] neg_hi:[0,1]
	v_pk_add_f32 v[6:7], v[6:7], v[138:139] op_sel_hi:[1,0] neg_lo:[0,1] neg_hi:[0,1]
	v_pk_add_f32 v[8:9], v[8:9], v[138:139] op_sel_hi:[1,0] neg_lo:[0,1] neg_hi:[0,1]
	v_pk_add_f32 v[10:11], v[10:11], v[138:139] op_sel_hi:[1,0] neg_lo:[0,1] neg_hi:[0,1]
	v_pk_add_f32 v[12:13], v[12:13], v[138:139] op_sel_hi:[1,0] neg_lo:[0,1] neg_hi:[0,1]
	v_pk_add_f32 v[14:15], v[14:15], v[138:139] op_sel_hi:[1,0] neg_lo:[0,1] neg_hi:[0,1]
	v_pk_add_f32 v[16:17], v[16:17], v[138:139] op_sel_hi:[1,0] neg_lo:[0,1] neg_hi:[0,1]
	v_pk_add_f32 v[18:19], v[18:19], v[138:139] op_sel_hi:[1,0] neg_lo:[0,1] neg_hi:[0,1]
	v_pk_add_f32 v[20:21], v[20:21], v[140:141] op_sel_hi:[1,0] neg_lo:[0,1] neg_hi:[0,1]
	v_pk_add_f32 v[22:23], v[22:23], v[140:141] op_sel_hi:[1,0] neg_lo:[0,1] neg_hi:[0,1]
	v_pk_add_f32 v[24:25], v[24:25], v[140:141] op_sel_hi:[1,0] neg_lo:[0,1] neg_hi:[0,1]
	v_pk_add_f32 v[26:27], v[26:27], v[140:141] op_sel_hi:[1,0] neg_lo:[0,1] neg_hi:[0,1]
	v_pk_add_f32 v[28:29], v[28:29], v[140:141] op_sel_hi:[1,0] neg_lo:[0,1] neg_hi:[0,1]
	v_pk_add_f32 v[30:31], v[30:31], v[140:141] op_sel_hi:[1,0] neg_lo:[0,1] neg_hi:[0,1]
	v_pk_add_f32 v[32:33], v[32:33], v[140:141] op_sel_hi:[1,0] neg_lo:[0,1] neg_hi:[0,1]
	v_pk_add_f32 v[34:35], v[34:35], v[140:141] op_sel_hi:[1,0] neg_lo:[0,1] neg_hi:[0,1]
	v_pk_add_f32 v[36:37], v[36:37], v[142:143] op_sel_hi:[1,0] neg_lo:[0,1] neg_hi:[0,1]
	v_pk_add_f32 v[38:39], v[38:39], v[142:143] op_sel_hi:[1,0] neg_lo:[0,1] neg_hi:[0,1]
	v_pk_add_f32 v[40:41], v[40:41], v[142:143] op_sel_hi:[1,0] neg_lo:[0,1] neg_hi:[0,1]
	v_pk_add_f32 v[42:43], v[42:43], v[142:143] op_sel_hi:[1,0] neg_lo:[0,1] neg_hi:[0,1]
	v_pk_add_f32 v[44:45], v[44:45], v[142:143] op_sel_hi:[1,0] neg_lo:[0,1] neg_hi:[0,1]
	v_pk_add_f32 v[46:47], v[46:47], v[142:143] op_sel_hi:[1,0] neg_lo:[0,1] neg_hi:[0,1]
	v_pk_add_f32 v[48:49], v[48:49], v[142:143] op_sel_hi:[1,0] neg_lo:[0,1] neg_hi:[0,1]
	v_pk_add_f32 v[50:51], v[50:51], v[142:143] op_sel_hi:[1,0] neg_lo:[0,1] neg_hi:[0,1]
	v_pk_add_f32 v[52:53], v[52:53], v[144:145] op_sel_hi:[1,0] neg_lo:[0,1] neg_hi:[0,1]
	v_pk_add_f32 v[54:55], v[54:55], v[144:145] op_sel_hi:[1,0] neg_lo:[0,1] neg_hi:[0,1]
	v_pk_add_f32 v[56:57], v[56:57], v[144:145] op_sel_hi:[1,0] neg_lo:[0,1] neg_hi:[0,1]
	v_pk_add_f32 v[58:59], v[58:59], v[144:145] op_sel_hi:[1,0] neg_lo:[0,1] neg_hi:[0,1]
	v_pk_add_f32 v[60:61], v[60:61], v[144:145] op_sel_hi:[1,0] neg_lo:[0,1] neg_hi:[0,1]
	v_pk_add_f32 v[62:63], v[62:63], v[144:145] op_sel_hi:[1,0] neg_lo:[0,1] neg_hi:[0,1]
	v_pk_add_f32 v[64:65], v[64:65], v[144:145] op_sel_hi:[1,0] neg_lo:[0,1] neg_hi:[0,1]
	v_pk_add_f32 v[66:67], v[66:67], v[144:145] op_sel_hi:[1,0] neg_lo:[0,1] neg_hi:[0,1]
	v_pk_mul_f32 v[146:147], v[4:5], v[4:5]
	v_pk_fma_f32 v[146:147], v[6:7], v[6:7], v[146:147]
	v_pk_fma_f32 v[146:147], v[8:9], v[8:9], v[146:147]
	v_pk_fma_f32 v[146:147], v[10:11], v[10:11], v[146:147]
	v_pk_fma_f32 v[146:147], v[12:13], v[12:13], v[146:147]
	v_pk_fma_f32 v[146:147], v[14:15], v[14:15], v[146:147]
	v_pk_fma_f32 v[146:147], v[16:17], v[16:17], v[146:147]
	v_pk_fma_f32 v[146:147], v[18:19], v[18:19], v[146:147]
	v_pk_mul_f32 v[148:149], v[20:21], v[20:21]
	v_pk_fma_f32 v[148:149], v[22:23], v[22:23], v[148:149]
	v_pk_fma_f32 v[148:149], v[24:25], v[24:25], v[148:149]
	v_pk_fma_f32 v[148:149], v[26:27], v[26:27], v[148:149]
	v_pk_fma_f32 v[148:149], v[28:29], v[28:29], v[148:149]
	v_pk_fma_f32 v[148:149], v[30:31], v[30:31], v[148:149]
	v_pk_fma_f32 v[148:149], v[32:33], v[32:33], v[148:149]
	v_pk_fma_f32 v[148:149], v[34:35], v[34:35], v[148:149]
	v_pk_mul_f32 v[150:151], v[36:37], v[36:37]
	v_pk_fma_f32 v[150:151], v[38:39], v[38:39], v[150:151]
	v_pk_fma_f32 v[150:151], v[40:41], v[40:41], v[150:151]
	v_pk_fma_f32 v[150:151], v[42:43], v[42:43], v[150:151]
	v_pk_fma_f32 v[150:151], v[44:45], v[44:45], v[150:151]
	v_pk_fma_f32 v[150:151], v[46:47], v[46:47], v[150:151]
	v_pk_fma_f32 v[150:151], v[48:49], v[48:49], v[150:151]
	v_pk_fma_f32 v[150:151], v[50:51], v[50:51], v[150:151]
	v_pk_mul_f32 v[152:153], v[52:53], v[52:53]
	v_pk_fma_f32 v[152:153], v[54:55], v[54:55], v[152:153]
	v_pk_fma_f32 v[152:153], v[56:57], v[56:57], v[152:153]
	v_pk_fma_f32 v[152:153], v[58:59], v[58:59], v[152:153]
	v_pk_fma_f32 v[152:153], v[60:61], v[60:61], v[152:153]
	v_pk_fma_f32 v[152:153], v[62:63], v[62:63], v[152:153]
	v_pk_fma_f32 v[152:153], v[64:65], v[64:65], v[152:153]
	v_pk_fma_f32 v[152:153], v[66:67], v[66:67], v[152:153]
	v_add_f32_e32 v146, v146, v147
	v_add_f32_e32 v148, v148, v149
	v_add_f32_e32 v150, v150, v151
	v_add_f32_e32 v152, v152, v153
	v_mov_b32_e32 v147, v146
	v_mov_b32_e32 v149, v148
	v_mov_b32_e32 v151, v150
	v_mov_b32_e32 v153, v152
	v_permlane32_swap_b32_e32 v146, v147
	v_permlane32_swap_b32_e32 v148, v149
	v_permlane32_swap_b32_e32 v150, v151
	v_permlane32_swap_b32_e32 v152, v153
	v_add_f32_e32 v146, v146, v147
	v_add_f32_e32 v148, v148, v149
	v_add_f32_e32 v150, v150, v151
	v_add_f32_e32 v152, v152, v153
	v_mov_b32_e32 v147, v146
	v_mov_b32_e32 v149, v148
	v_mov_b32_e32 v151, v150
	v_mov_b32_e32 v153, v152
	v_permlane16_swap_b32_e32 v146, v147
	v_permlane16_swap_b32_e32 v148, v149
	v_permlane16_swap_b32_e32 v150, v151
	v_permlane16_swap_b32_e32 v152, v153
	v_add_f32_e32 v146, v146, v147
	v_add_f32_e32 v148, v148, v149
	v_add_f32_e32 v150, v150, v151
	v_add_f32_e32 v152, v152, v153
	v_add_f32_dpp v146, v146, v146 row_ror:8 row_mask:0xf bank_mask:0xf
	v_add_f32_dpp v148, v148, v148 row_ror:8 row_mask:0xf bank_mask:0xf
	v_add_f32_dpp v150, v150, v150 row_ror:8 row_mask:0xf bank_mask:0xf
	v_add_f32_dpp v152, v152, v152 row_ror:8 row_mask:0xf bank_mask:0xf
	v_add_f32_dpp v146, v146, v146 row_ror:4 row_mask:0xf bank_mask:0xf
	v_add_f32_dpp v148, v148, v148 row_ror:4 row_mask:0xf bank_mask:0xf
	v_add_f32_dpp v150, v150, v150 row_ror:4 row_mask:0xf bank_mask:0xf
	v_add_f32_dpp v152, v152, v152 row_ror:4 row_mask:0xf bank_mask:0xf
	v_add_f32_dpp v146, v146, v146 row_ror:2 row_mask:0xf bank_mask:0xf
	v_add_f32_dpp v148, v148, v148 row_ror:2 row_mask:0xf bank_mask:0xf
	v_add_f32_dpp v150, v150, v150 row_ror:2 row_mask:0xf bank_mask:0xf
	v_add_f32_dpp v152, v152, v152 row_ror:2 row_mask:0xf bank_mask:0xf
	v_add_f32_dpp v146, v146, v146 row_ror:1 row_mask:0xf bank_mask:0xf
	v_add_f32_dpp v148, v148, v148 row_ror:1 row_mask:0xf bank_mask:0xf
	v_add_f32_dpp v150, v150, v150 row_ror:1 row_mask:0xf bank_mask:0xf
	v_add_f32_dpp v152, v152, v152 row_ror:1 row_mask:0xf bank_mask:0xf
	v_fma_f32 v146, v146, s46, v154
	v_fma_f32 v148, v148, s46, v154
	v_fma_f32 v150, v150, s46, v154
	v_fma_f32 v152, v152, s46, v154
	v_mul_f32_e32 v155, 0x4b800000, v146
	v_cmp_gt_f32_e32 vcc, s29, v146
	s_nop 1
	v_cndmask_b32_e32 v155, v146, v155, vcc
	v_rsq_f32_e32 v155, v155
	s_nop 0
	v_mul_f32_e32 v156, 0x45800000, v155
	v_cndmask_b32_e32 v146, v155, v156, vcc
	v_mul_f32_e32 v155, 0x4b800000, v148
	v_cmp_gt_f32_e32 vcc, s29, v148
	s_nop 1
	v_cndmask_b32_e32 v155, v148, v155, vcc
	v_rsq_f32_e32 v155, v155
	s_nop 0
	v_mul_f32_e32 v156, 0x45800000, v155
	v_cndmask_b32_e32 v148, v155, v156, vcc
	v_mul_f32_e32 v155, 0x4b800000, v150
	v_cmp_gt_f32_e32 vcc, s29, v150
	s_nop 1
	v_cndmask_b32_e32 v155, v150, v155, vcc
	v_rsq_f32_e32 v155, v155
	s_nop 0
	v_mul_f32_e32 v156, 0x45800000, v155
	v_cndmask_b32_e32 v150, v155, v156, vcc
	v_mul_f32_e32 v155, 0x4b800000, v152
	v_cmp_gt_f32_e32 vcc, s29, v152
	s_nop 1
	v_cndmask_b32_e32 v155, v152, v155, vcc
	v_rsq_f32_e32 v155, v155
	s_nop 0
	v_mul_f32_e32 v156, 0x45800000, v155
	v_cndmask_b32_e32 v152, v155, v156, vcc
	s_waitcnt vmcnt(0)
	v_pk_add_f32 v[100:101], v[100:101], 1.0 op_sel_hi:[1,0]
	v_pk_add_f32 v[102:103], v[102:103], 1.0 op_sel_hi:[1,0]
	v_pk_add_f32 v[104:105], v[104:105], 1.0 op_sel_hi:[1,0]
	v_pk_add_f32 v[106:107], v[106:107], 1.0 op_sel_hi:[1,0]
	v_pk_add_f32 v[108:109], v[108:109], 1.0 op_sel_hi:[1,0]
	v_pk_add_f32 v[110:111], v[110:111], 1.0 op_sel_hi:[1,0]
	v_pk_add_f32 v[112:113], v[112:113], 1.0 op_sel_hi:[1,0]
	v_pk_add_f32 v[114:115], v[114:115], 1.0 op_sel_hi:[1,0]
	v_pk_mul_f32 v[182:183], v[4:5], v[146:147] op_sel_hi:[1,0]
	v_pk_mul_f32 v[184:185], v[6:7], v[146:147] op_sel_hi:[1,0]
	v_pk_mul_f32 v[186:187], v[8:9], v[146:147] op_sel_hi:[1,0]
	v_pk_mul_f32 v[188:189], v[10:11], v[146:147] op_sel_hi:[1,0]
	v_pk_fma_f32 v[158:159], v[68:69], v[182:183], v[84:85]
	v_pk_fma_f32 v[160:161], v[70:71], v[184:185], v[86:87]
	v_pk_fma_f32 v[162:163], v[72:73], v[186:187], v[88:89]
	v_pk_fma_f32 v[164:165], v[74:75], v[188:189], v[90:91]
	global_store_dwordx4 v134, v[158:161], s[4:5]
	global_store_dwordx4 v134, v[162:165], s[4:5] offset:16
	v_pk_fma_f32 v[182:183], v[158:159], v[100:101], v[118:119]
	v_pk_fma_f32 v[184:185], v[160:161], v[102:103], v[120:121]
	v_pk_fma_f32 v[186:187], v[162:163], v[104:105], v[122:123]
	v_pk_fma_f32 v[188:189], v[164:165], v[106:107], v[124:125]
	v_cvt_pk_bf16_f32 v174, v182, v183
	v_cvt_pk_bf16_f32 v175, v184, v185
	v_cvt_pk_bf16_f32 v176, v186, v187
	v_cvt_pk_bf16_f32 v177, v188, v189
	global_store_dwordx4 v2, v[174:177], s[12:13]
	v_pk_mul_f32 v[182:183], v[12:13], v[146:147] op_sel_hi:[1,0]
	v_pk_mul_f32 v[184:185], v[14:15], v[146:147] op_sel_hi:[1,0]
	v_pk_mul_f32 v[186:187], v[16:17], v[146:147] op_sel_hi:[1,0]
	v_pk_mul_f32 v[188:189], v[18:19], v[146:147] op_sel_hi:[1,0]
	v_pk_fma_f32 v[166:167], v[76:77], v[182:183], v[92:93]
	v_pk_fma_f32 v[168:169], v[78:79], v[184:185], v[94:95]
	v_pk_fma_f32 v[170:171], v[80:81], v[186:187], v[96:97]
	v_pk_fma_f32 v[172:173], v[82:83], v[188:189], v[98:99]
	global_store_dwordx4 v134, v[166:169], s[4:5] offset:2048
	global_store_dwordx4 v134, v[170:173], s[4:5] offset:2064
	v_pk_fma_f32 v[182:183], v[166:167], v[108:109], v[126:127]
	v_pk_fma_f32 v[184:185], v[168:169], v[110:111], v[128:129]
	v_pk_fma_f32 v[186:187], v[170:171], v[112:113], v[130:131]
	v_pk_fma_f32 v[188:189], v[172:173], v[114:115], v[132:133]
	v_cvt_pk_bf16_f32 v178, v182, v183
	v_cvt_pk_bf16_f32 v179, v184, v185
	v_cvt_pk_bf16_f32 v180, v186, v187
	v_cvt_pk_bf16_f32 v181, v188, v189
	global_store_dwordx4 v2, v[178:181], s[12:13] offset:1024
	v_pk_mul_f32 v[182:183], v[20:21], v[148:149] op_sel_hi:[1,0]
	v_pk_mul_f32 v[184:185], v[22:23], v[148:149] op_sel_hi:[1,0]
	v_pk_mul_f32 v[186:187], v[24:25], v[148:149] op_sel_hi:[1,0]
	v_pk_mul_f32 v[188:189], v[26:27], v[148:149] op_sel_hi:[1,0]
	v_pk_fma_f32 v[158:159], v[68:69], v[182:183], v[84:85]
	v_pk_fma_f32 v[160:161], v[70:71], v[184:185], v[86:87]
	v_pk_fma_f32 v[162:163], v[72:73], v[186:187], v[88:89]
	v_pk_fma_f32 v[164:165], v[74:75], v[188:189], v[90:91]
	global_store_dwordx4 v135, v[158:161], s[4:5]
	global_store_dwordx4 v135, v[162:165], s[4:5] offset:16
	v_pk_fma_f32 v[182:183], v[158:159], v[100:101], v[118:119]
	v_pk_fma_f32 v[184:185], v[160:161], v[102:103], v[120:121]
	v_pk_fma_f32 v[186:187], v[162:163], v[104:105], v[122:123]
	v_pk_fma_f32 v[188:189], v[164:165], v[106:107], v[124:125]
	v_cvt_pk_bf16_f32 v174, v182, v183
	v_cvt_pk_bf16_f32 v175, v184, v185
	v_cvt_pk_bf16_f32 v176, v186, v187
	v_cvt_pk_bf16_f32 v177, v188, v189
	global_store_dwordx4 v2, v[174:177], s[12:13] offset:2048
	v_pk_mul_f32 v[182:183], v[28:29], v[148:149] op_sel_hi:[1,0]
	v_pk_mul_f32 v[184:185], v[30:31], v[148:149] op_sel_hi:[1,0]
	v_pk_mul_f32 v[186:187], v[32:33], v[148:149] op_sel_hi:[1,0]
	v_pk_mul_f32 v[188:189], v[34:35], v[148:149] op_sel_hi:[1,0]
	v_pk_fma_f32 v[166:167], v[76:77], v[182:183], v[92:93]
	v_pk_fma_f32 v[168:169], v[78:79], v[184:185], v[94:95]
	v_pk_fma_f32 v[170:171], v[80:81], v[186:187], v[96:97]
	v_pk_fma_f32 v[172:173], v[82:83], v[188:189], v[98:99]
	global_store_dwordx4 v135, v[166:169], s[4:5] offset:2048
	global_store_dwordx4 v135, v[170:173], s[4:5] offset:2064
	v_pk_fma_f32 v[182:183], v[166:167], v[108:109], v[126:127]
	v_pk_fma_f32 v[184:185], v[168:169], v[110:111], v[128:129]
	v_pk_fma_f32 v[186:187], v[170:171], v[112:113], v[130:131]
	v_pk_fma_f32 v[188:189], v[172:173], v[114:115], v[132:133]
	v_cvt_pk_bf16_f32 v178, v182, v183
	v_cvt_pk_bf16_f32 v179, v184, v185
	v_cvt_pk_bf16_f32 v180, v186, v187
	v_cvt_pk_bf16_f32 v181, v188, v189
	global_store_dwordx4 v2, v[178:181], s[12:13] offset:3072
	v_pk_mul_f32 v[182:183], v[36:37], v[150:151] op_sel_hi:[1,0]
	v_pk_mul_f32 v[184:185], v[38:39], v[150:151] op_sel_hi:[1,0]
	v_pk_mul_f32 v[186:187], v[40:41], v[150:151] op_sel_hi:[1,0]
	v_pk_mul_f32 v[188:189], v[42:43], v[150:151] op_sel_hi:[1,0]
	v_pk_fma_f32 v[158:159], v[68:69], v[182:183], v[84:85]
	v_pk_fma_f32 v[160:161], v[70:71], v[184:185], v[86:87]
	v_pk_fma_f32 v[162:163], v[72:73], v[186:187], v[88:89]
	v_pk_fma_f32 v[164:165], v[74:75], v[188:189], v[90:91]
	global_store_dwordx4 v136, v[158:161], s[4:5]
	global_store_dwordx4 v136, v[162:165], s[4:5] offset:16
	v_pk_fma_f32 v[182:183], v[158:159], v[100:101], v[118:119]
	v_pk_fma_f32 v[184:185], v[160:161], v[102:103], v[120:121]
	v_pk_fma_f32 v[186:187], v[162:163], v[104:105], v[122:123]
	v_pk_fma_f32 v[188:189], v[164:165], v[106:107], v[124:125]
	v_cvt_pk_bf16_f32 v174, v182, v183
	v_cvt_pk_bf16_f32 v175, v184, v185
	v_cvt_pk_bf16_f32 v176, v186, v187
	v_cvt_pk_bf16_f32 v177, v188, v189
	global_store_dwordx4 v3, v[174:177], s[12:13]
	v_pk_mul_f32 v[182:183], v[44:45], v[150:151] op_sel_hi:[1,0]
	v_pk_mul_f32 v[184:185], v[46:47], v[150:151] op_sel_hi:[1,0]
	v_pk_mul_f32 v[186:187], v[48:49], v[150:151] op_sel_hi:[1,0]
	v_pk_mul_f32 v[188:189], v[50:51], v[150:151] op_sel_hi:[1,0]
	v_pk_fma_f32 v[166:167], v[76:77], v[182:183], v[92:93]
	v_pk_fma_f32 v[168:169], v[78:79], v[184:185], v[94:95]
	v_pk_fma_f32 v[170:171], v[80:81], v[186:187], v[96:97]
	v_pk_fma_f32 v[172:173], v[82:83], v[188:189], v[98:99]
	global_store_dwordx4 v136, v[166:169], s[4:5] offset:2048
	global_store_dwordx4 v136, v[170:173], s[4:5] offset:2064
	v_pk_fma_f32 v[182:183], v[166:167], v[108:109], v[126:127]
	v_pk_fma_f32 v[184:185], v[168:169], v[110:111], v[128:129]
	v_pk_fma_f32 v[186:187], v[170:171], v[112:113], v[130:131]
	v_pk_fma_f32 v[188:189], v[172:173], v[114:115], v[132:133]
	v_cvt_pk_bf16_f32 v178, v182, v183
	v_cvt_pk_bf16_f32 v179, v184, v185
	v_cvt_pk_bf16_f32 v180, v186, v187
	v_cvt_pk_bf16_f32 v181, v188, v189
	global_store_dwordx4 v3, v[178:181], s[12:13] offset:1024
	v_pk_mul_f32 v[182:183], v[52:53], v[152:153] op_sel_hi:[1,0]
	v_pk_mul_f32 v[184:185], v[54:55], v[152:153] op_sel_hi:[1,0]
	v_pk_mul_f32 v[186:187], v[56:57], v[152:153] op_sel_hi:[1,0]
	v_pk_mul_f32 v[188:189], v[58:59], v[152:153] op_sel_hi:[1,0]
	v_pk_fma_f32 v[158:159], v[68:69], v[182:183], v[84:85]
	v_pk_fma_f32 v[160:161], v[70:71], v[184:185], v[86:87]
	v_pk_fma_f32 v[162:163], v[72:73], v[186:187], v[88:89]
	v_pk_fma_f32 v[164:165], v[74:75], v[188:189], v[90:91]
	global_store_dwordx4 v137, v[158:161], s[4:5]
	global_store_dwordx4 v137, v[162:165], s[4:5] offset:16
	v_pk_fma_f32 v[182:183], v[158:159], v[100:101], v[118:119]
	v_pk_fma_f32 v[184:185], v[160:161], v[102:103], v[120:121]
	v_pk_fma_f32 v[186:187], v[162:163], v[104:105], v[122:123]
	v_pk_fma_f32 v[188:189], v[164:165], v[106:107], v[124:125]
	v_cvt_pk_bf16_f32 v174, v182, v183
	v_cvt_pk_bf16_f32 v175, v184, v185
	v_cvt_pk_bf16_f32 v176, v186, v187
	v_cvt_pk_bf16_f32 v177, v188, v189
	global_store_dwordx4 v3, v[174:177], s[12:13] offset:2048
	v_pk_mul_f32 v[182:183], v[60:61], v[152:153] op_sel_hi:[1,0]
	v_pk_mul_f32 v[184:185], v[62:63], v[152:153] op_sel_hi:[1,0]
	v_pk_mul_f32 v[186:187], v[64:65], v[152:153] op_sel_hi:[1,0]
	v_pk_mul_f32 v[188:189], v[66:67], v[152:153] op_sel_hi:[1,0]
	v_pk_fma_f32 v[166:167], v[76:77], v[182:183], v[92:93]
	v_pk_fma_f32 v[168:169], v[78:79], v[184:185], v[94:95]
	v_pk_fma_f32 v[170:171], v[80:81], v[186:187], v[96:97]
	v_pk_fma_f32 v[172:173], v[82:83], v[188:189], v[98:99]
	global_store_dwordx4 v137, v[166:169], s[4:5] offset:2048
	global_store_dwordx4 v137, v[170:173], s[4:5] offset:2064
	v_pk_fma_f32 v[182:183], v[166:167], v[108:109], v[126:127]
	v_pk_fma_f32 v[184:185], v[168:169], v[110:111], v[128:129]
	v_pk_fma_f32 v[186:187], v[170:171], v[112:113], v[130:131]
	v_pk_fma_f32 v[188:189], v[172:173], v[114:115], v[132:133]
	v_cvt_pk_bf16_f32 v178, v182, v183
	v_cvt_pk_bf16_f32 v179, v184, v185
	v_cvt_pk_bf16_f32 v180, v186, v187
	v_cvt_pk_bf16_f32 v181, v188, v189
	global_store_dwordx4 v3, v[178:181], s[12:13] offset:3072
	s_add_i32 s0, s0, 32
	s_branch .Lln1_loop
.Lln1_end:
.LBB0_1032:
	v_writelane_b32 v255, s82, 18
	s_nop 1
	v_writelane_b32 v255, s83, 19
	s_mov_b64 s[82:83], 0x20000
	s_or_b64 exec, exec, s[6:7]
	s_mov_b32 s0, s91
	s_mov_b32 s70, 0
	s_waitcnt vmcnt(0)
	s_waitcnt lgkmcnt(0)
	v_or_b32_e32 v0, s0, v230
	v_cmp_eq_u32_e32 vcc, 0, v0
	s_barrier
	s_and_saveexec_b64 s[0:1], vcc
	s_cbranch_execz .LBB0_1076
	v_writelane_b32 v2, s4, 1
	v_writelane_b32 v2, s5, 2
	v_writelane_b32 v2, s6, 3
	v_writelane_b32 v2, s7, 4
	v_readlane_b32 s4, v254, 45
	v_readlane_b32 s5, v254, 46
	s_getreg_b32 s6, hwreg(HW_REG_XCC_ID, 0, 4)
	s_nop 0
	v_mov_b32_e32 v0, 0x20010
	ds_read_b32 v3, v0
	ds_read_b32 v4, v0 offset:4
	ds_read_b32 v5, v0 offset:8
	s_and_b32 s6, s6, 15
	s_lshl_b32 s6, s6, 8
	v_mov_b32_e32 v13, 0x3400
	v_mov_b32_e32 v8, 1
	v_mov_b32_e32 v14, 0
	s_waitcnt lgkmcnt(0)
	s_add_u32 s4, s4, 0xee42000
	s_addc_u32 s5, s5, 0
	v_mov_b32_e32 v6, s6
	v_add_u32_e32 v7, 0x400, v6
	v_add_u32_e32 v6, 0x1400, v6
	buffer_inv sc1
	global_atomic_add v9, v6, v8, s[4:5] sc0
	v_add_u32_e32 v10, 1, v5
	v_mul_lo_u32 v11, v10, v3
	v_mul_lo_u32 v12, v10, v4
	s_waitcnt vmcnt(0)
	v_add_u32_e32 v9, 1, v9
	v_cmp_eq_u32_e32 vcc, v9, v11
	s_cbranch_vccz .Lhb_poll_7
	buffer_wbl2 sc1
	s_waitcnt vmcnt(0)
	global_atomic_add v13, v8, s[4:5]
